# attention QK blocks re-pipelined: 10 K-fragment reads up front, counted lgkmcnt(8), same per-accumulator MFMA order; on top of address diets + static prio
# speedup vs baseline: 1.0036x; 1.0007x over previous
.LBB0_185:
	s_waitcnt vmcnt(0)
	s_barrier
	v_mbcnt_lo_u32_b32 v192, -1, 0
	v_mbcnt_hi_u32_b32 v192, -1, v192
	s_add_i32 s35, 0, 0x10000
	s_add_i32 s37, s35, s61
	s_add_i32 s92, s37, 0x4000
	s_add_u32 s98, s8, s14
	s_addc_u32 s99, s9, s15
	s_add_u32 s100, s8, s28
	s_addc_u32 s101, s9, s29
	s_mov_b32 m0, s37
	s_add_i32 s35, s35, s65
	global_load_lds_dwordx4 v251, s[98:99]
	s_mov_b32 m0, s92
	s_add_i32 s93, s35, 0x4000
	global_load_lds_dwordx4 v251, s[100:101]
	s_mov_b32 m0, s35
	s_add_i32 s36, s68, s79
	global_load_lds_dwordx4 v252, s[98:99]
	s_mov_b32 m0, s93
	s_add_i32 s90, s36, 64
	global_load_lds_dwordx4 v252, s[100:101]
	s_add_i32 s34, s79, 63
	s_mul_hi_i32 s91, s90, 0xa000
	s_mul_i32 s90, s90, 0xa000
	s_add_u32 s90, s82, s90
	s_addc_u32 s91, s83, s91
	s_add_u32 s98, s90, 0x80
	s_addc_u32 s99, s91, 0
	s_add_i32 s94, s47, s70
	s_mov_b32 m0, s94
	s_add_i32 s95, s94, 0x400
	global_load_lds_dwordx4 v253, s[90:91]
	s_mov_b32 m0, s95
	s_add_i32 s96, s47, s74
	global_load_lds_dwordx4 v253, s[98:99]
	s_mov_b32 m0, s96
	s_add_i32 s97, s47, s77
	global_load_lds_dwordx4 v254, s[90:91]
	s_mov_b32 m0, s97
	v_ashrrev_i32_e32 v188, 5, v192
	global_load_lds_dwordx4 v254, s[98:99]
	v_and_b32_e32 v193, 31, v192
	v_lshlrev_b32_e32 v189, 4, v192
	v_lshlrev_b32_e32 v191, 4, v188
	v_lshlrev_b32_e32 v190, 8, v193
	s_cmp_le_u32 s34, s59
	v_bitop3_b32 v2, v189, v191, s48 bitop3:0x6c
	v_add3_u32 v6, s84, v2, v190
	v_add_u32_e32 v7, 32, v191
	v_bitop3_b32 v7, v7, v189, s48 bitop3:0x78
	v_add3_u32 v250, s84, v7, v190
	v_add_u32_e32 v7, 64, v191
	v_bitop3_b32 v7, v7, v189, s48 bitop3:0x78
	v_add3_u32 v222, s84, v7, v190
	v_add_u32_e32 v7, 0x60, v191
	v_bitop3_b32 v7, v7, v189, s48 bitop3:0x78
	v_add3_u32 v190, s84, v7, v190
	v_add_u32_e32 v189, s81, v189
	ds_read_b128 v[2:5], v6
	ds_read_b128 v[194:197], v6 offset:8192
	ds_read_b128 v[198:201], v250
	ds_read_b128 v[202:205], v250 offset:8192
	ds_read_b128 v[206:209], v222
	ds_read_b128 v[210:213], v222 offset:8192
	ds_read_b128 v[214:217], v190
	ds_read_b128 v[218:221], v190 offset:8192
	ds_read_b128 v[226:229], v6 offset:128
	ds_read_b128 v[230:233], v6 offset:8320
	s_waitcnt lgkmcnt(9)
	v_mfma_f32_32x32x16_bf16 v[18:33], v[2:5], v[34:37], 0
	s_waitcnt lgkmcnt(8)
	v_mfma_f32_32x32x16_bf16 v[2:17], v[194:197], v[34:37], 0
	ds_read_b128 v[194:197], v250 offset:128
	s_waitcnt lgkmcnt(8)
	v_mfma_f32_32x32x16_bf16 v[18:33], v[198:201], v[38:41], v[18:33]
	ds_read_b128 v[198:201], v250 offset:8320
	s_waitcnt lgkmcnt(8)
	v_mfma_f32_32x32x16_bf16 v[2:17], v[202:205], v[38:41], v[2:17]
	ds_read_b128 v[202:205], v222 offset:128
	s_waitcnt lgkmcnt(8)
	v_mfma_f32_32x32x16_bf16 v[18:33], v[206:209], v[42:45], v[18:33]
	ds_read_b128 v[206:209], v222 offset:8320
	s_waitcnt lgkmcnt(8)
	v_mfma_f32_32x32x16_bf16 v[2:17], v[210:213], v[42:45], v[2:17]
	ds_read_b128 v[210:213], v190 offset:128
	s_waitcnt lgkmcnt(8)
	v_mfma_f32_32x32x16_bf16 v[18:33], v[214:217], v[46:49], v[18:33]
	ds_read_b128 v[214:217], v190 offset:8320
	s_waitcnt lgkmcnt(8)
	v_mfma_f32_32x32x16_bf16 v[2:17], v[218:221], v[46:49], v[2:17]
	ds_read_b128 v[218:221], v189
	s_waitcnt lgkmcnt(8)
	v_mfma_f32_32x32x16_bf16 v[18:33], v[226:229], v[50:53], v[18:33]
	ds_read_b128 v[226:229], v189 offset:1024
	s_waitcnt lgkmcnt(8)
	v_mfma_f32_32x32x16_bf16 v[2:17], v[230:233], v[50:53], v[2:17]
	s_waitcnt lgkmcnt(7)
	v_mfma_f32_32x32x16_bf16 v[18:33], v[194:197], v[54:57], v[18:33]
	s_waitcnt lgkmcnt(6)
	v_mfma_f32_32x32x16_bf16 v[2:17], v[198:201], v[54:57], v[2:17]
	s_waitcnt lgkmcnt(1)
	v_mfma_f32_32x32x16_bf16 v[18:33], v[202:205], v[218:221], v[18:33]
	v_mfma_f32_32x32x16_bf16 v[2:17], v[206:209], v[218:221], v[2:17]
	s_waitcnt lgkmcnt(0)
	v_mfma_f32_32x32x16_bf16 v[18:33], v[210:213], v[226:229], v[18:33]
	v_mfma_f32_32x32x16_bf16 v[2:17], v[214:217], v[226:229], v[2:17]
	s_cbranch_scc1 .LBB0_187
	v_lshlrev_b32_e32 v188, 2, v188
	v_sub_u32_e32 v188, v193, v188
	v_add_u32_e32 v188, s86, v188
	v_add_u32_e32 v189, 0x80000001, v188
	v_cmp_gt_u32_e32 vcc, s46, v189
	s_nop 4
	v_cndmask_b32_e32 v18, v225, v18, vcc
	v_cmp_lt_i32_e32 vcc, 31, v189
	s_nop 1
	v_cndmask_b32_e32 v2, v225, v2, vcc
	v_cmp_lt_i32_e32 vcc, 0, v189
	v_subrev_u32_e32 v189, 31, v188
	s_nop 0
	v_cndmask_b32_e32 v19, v225, v19, vcc
	v_cmp_lt_u32_e32 vcc, s49, v189
	v_subrev_u32_e32 v189, 32, v188
	s_nop 0
	v_cndmask_b32_e32 v3, v225, v3, vcc
	v_cmp_lt_u32_e32 vcc, s49, v188
	s_nop 1
	v_cndmask_b32_e32 v20, v225, v20, vcc
	v_cmp_lt_u32_e32 vcc, s49, v189
	v_add_u32_e32 v189, -1, v188
	s_nop 0
	v_cndmask_b32_e32 v4, v225, v4, vcc
	v_cmp_lt_u32_e32 vcc, s49, v189
	v_subrev_u32_e32 v189, 33, v188
	s_nop 0
	v_cndmask_b32_e32 v21, v225, v21, vcc
	v_cmp_lt_u32_e32 vcc, s49, v189
	v_add_u32_e32 v189, -6, v188
	s_nop 0
	v_cndmask_b32_e32 v5, v225, v5, vcc
	v_cmp_lt_u32_e32 vcc, s49, v189
	v_subrev_u32_e32 v189, 38, v188
	s_nop 0
	v_cndmask_b32_e32 v22, v225, v22, vcc
	v_cmp_lt_u32_e32 vcc, s49, v189
	v_add_u32_e32 v189, -7, v188
	s_nop 0
	v_cndmask_b32_e32 v6, v225, v6, vcc
	v_cmp_lt_u32_e32 vcc, s49, v189
	v_subrev_u32_e32 v189, 39, v188
	s_nop 0
	v_cndmask_b32_e32 v23, v225, v23, vcc
	v_cmp_lt_u32_e32 vcc, s49, v189
	v_add_u32_e32 v189, -8, v188
	s_nop 0
	v_cndmask_b32_e32 v7, v225, v7, vcc
	v_cmp_lt_u32_e32 vcc, s49, v189
	v_subrev_u32_e32 v189, 40, v188
	s_nop 0
	v_cndmask_b32_e32 v24, v225, v24, vcc
	v_cmp_lt_u32_e32 vcc, s49, v189
	v_add_u32_e32 v189, -9, v188
	s_nop 0
	v_cndmask_b32_e32 v8, v225, v8, vcc
	v_cmp_lt_u32_e32 vcc, s49, v189
	v_subrev_u32_e32 v189, 41, v188
	s_nop 0
	v_cndmask_b32_e32 v25, v225, v25, vcc
	v_cmp_lt_u32_e32 vcc, s49, v189
	v_add_u32_e32 v189, -14, v188
	s_nop 0
	v_cndmask_b32_e32 v9, v225, v9, vcc
	v_cmp_lt_u32_e32 vcc, s49, v189
	v_subrev_u32_e32 v189, 46, v188
	s_nop 0
	v_cndmask_b32_e32 v26, v225, v26, vcc
	v_cmp_lt_u32_e32 vcc, s49, v189
	v_add_u32_e32 v189, -15, v188
	s_nop 0
	v_cndmask_b32_e32 v10, v225, v10, vcc
	v_cmp_lt_u32_e32 vcc, s49, v189
	v_subrev_u32_e32 v189, 47, v188
	s_nop 0
	v_cndmask_b32_e32 v27, v225, v27, vcc
	v_cmp_lt_u32_e32 vcc, s49, v189
	v_add_u32_e32 v189, -16, v188
	s_nop 0
	v_cndmask_b32_e32 v11, v225, v11, vcc
	v_cmp_lt_u32_e32 vcc, s49, v189
	v_subrev_u32_e32 v189, 48, v188
	s_nop 0
	v_cndmask_b32_e32 v28, v225, v28, vcc
	v_cmp_lt_u32_e32 vcc, s49, v189
	v_subrev_u32_e32 v189, 17, v188
	s_nop 0
	v_cndmask_b32_e32 v12, v225, v12, vcc
	v_cmp_lt_u32_e32 vcc, s49, v189
	v_subrev_u32_e32 v189, 49, v188
	s_nop 0
	v_cndmask_b32_e32 v29, v225, v29, vcc
	v_cmp_lt_u32_e32 vcc, s49, v189
	v_subrev_u32_e32 v189, 22, v188
	s_nop 0
	v_cndmask_b32_e32 v13, v225, v13, vcc
	v_cmp_lt_u32_e32 vcc, s49, v189
	v_subrev_u32_e32 v189, 54, v188
	s_nop 0
	v_cndmask_b32_e32 v30, v225, v30, vcc
	v_cmp_lt_u32_e32 vcc, s49, v189
	v_subrev_u32_e32 v189, 23, v188
	s_nop 0
	v_cndmask_b32_e32 v14, v225, v14, vcc
	v_cmp_lt_u32_e32 vcc, s49, v189
	v_subrev_u32_e32 v189, 55, v188
	s_nop 0
	v_cndmask_b32_e32 v31, v225, v31, vcc
	v_cmp_lt_u32_e32 vcc, s49, v189
	v_subrev_u32_e32 v189, 24, v188
	s_nop 0
	v_cndmask_b32_e32 v15, v225, v15, vcc
	v_cmp_lt_u32_e32 vcc, s49, v189
	v_subrev_u32_e32 v189, 56, v188
	s_nop 0
	v_cndmask_b32_e32 v32, v225, v32, vcc
	v_cmp_lt_u32_e32 vcc, s49, v189
	v_subrev_u32_e32 v189, 25, v188
	v_subrev_u32_e32 v188, 57, v188
	v_cndmask_b32_e32 v16, v225, v16, vcc
	v_cmp_lt_u32_e32 vcc, s49, v189
	s_nop 1
	v_cndmask_b32_e32 v33, v225, v33, vcc
	v_cmp_lt_u32_e32 vcc, s49, v188
	s_nop 1
	v_cndmask_b32_e32 v17, v225, v17, vcc

.LBB0_194:
	v_ashrrev_i32_e32 v193, 5, v192
	v_and_b32_e32 v194, 31, v192
	v_lshlrev_b32_e32 v195, 4, v192
	v_lshlrev_b32_e32 v221, 4, v193
	v_lshlrev_b32_e32 v220, 8, v194
	s_add_i32 s36, s79, 0x7f
	s_cmp_le_u32 s36, s59
	v_bitop3_b32 v2, v195, v221, s48 bitop3:0x6c
	v_add3_u32 v6, s85, v2, v220
	v_add_u32_e32 v7, 32, v221
	v_bitop3_b32 v7, v7, v195, s48 bitop3:0x78
	v_add3_u32 v250, s85, v7, v220
	v_add_u32_e32 v7, 64, v221
	v_bitop3_b32 v7, v7, v195, s48 bitop3:0x78
	v_add3_u32 v222, s85, v7, v220
	v_add_u32_e32 v7, 0x60, v221
	v_bitop3_b32 v7, v7, v195, s48 bitop3:0x78
	v_add3_u32 v220, s85, v7, v220
	v_add_u32_e32 v195, s81, v195
	ds_read_b128 v[2:5], v6
	ds_read_b128 v[196:199], v6 offset:8192
	ds_read_b128 v[200:203], v250
	ds_read_b128 v[204:207], v250 offset:8192
	ds_read_b128 v[208:211], v222
	ds_read_b128 v[212:215], v222 offset:8192
	ds_read_b128 v[216:219], v220
	ds_read_b128 v[226:229], v220 offset:8192
	ds_read_b128 v[230:233], v6 offset:128
	ds_read_b128 v[234:237], v6 offset:8320
	s_waitcnt lgkmcnt(9)
	v_mfma_f32_32x32x16_bf16 v[18:33], v[2:5], v[34:37], 0
	s_waitcnt lgkmcnt(8)
	v_mfma_f32_32x32x16_bf16 v[2:17], v[196:199], v[34:37], 0
	ds_read_b128 v[196:199], v250 offset:128
	s_waitcnt lgkmcnt(8)
	v_mfma_f32_32x32x16_bf16 v[18:33], v[200:203], v[38:41], v[18:33]
	ds_read_b128 v[200:203], v250 offset:8320
	s_waitcnt lgkmcnt(8)
	v_mfma_f32_32x32x16_bf16 v[2:17], v[204:207], v[38:41], v[2:17]
	ds_read_b128 v[204:207], v222 offset:128
	s_waitcnt lgkmcnt(8)
	v_mfma_f32_32x32x16_bf16 v[18:33], v[208:211], v[42:45], v[18:33]
	ds_read_b128 v[208:211], v222 offset:8320
	s_waitcnt lgkmcnt(8)
	v_mfma_f32_32x32x16_bf16 v[2:17], v[212:215], v[42:45], v[2:17]
	ds_read_b128 v[212:215], v220 offset:128
	s_waitcnt lgkmcnt(8)
	v_mfma_f32_32x32x16_bf16 v[18:33], v[216:219], v[46:49], v[18:33]
	ds_read_b128 v[216:219], v220 offset:8320
	s_waitcnt lgkmcnt(8)
	v_mfma_f32_32x32x16_bf16 v[2:17], v[226:229], v[46:49], v[2:17]
	ds_read_b128 v[226:229], v195
	s_waitcnt lgkmcnt(8)
	v_mfma_f32_32x32x16_bf16 v[18:33], v[230:233], v[50:53], v[18:33]
	ds_read_b128 v[230:233], v195 offset:1024
	s_waitcnt lgkmcnt(8)
	v_mfma_f32_32x32x16_bf16 v[2:17], v[234:237], v[50:53], v[2:17]
	s_waitcnt lgkmcnt(7)
	v_mfma_f32_32x32x16_bf16 v[18:33], v[196:199], v[54:57], v[18:33]
	s_waitcnt lgkmcnt(6)
	v_mfma_f32_32x32x16_bf16 v[2:17], v[200:203], v[54:57], v[2:17]
	s_waitcnt lgkmcnt(1)
	v_mfma_f32_32x32x16_bf16 v[18:33], v[204:207], v[226:229], v[18:33]
	v_mfma_f32_32x32x16_bf16 v[2:17], v[208:211], v[226:229], v[2:17]
	s_waitcnt lgkmcnt(0)
	v_mfma_f32_32x32x16_bf16 v[18:33], v[212:215], v[230:233], v[18:33]
	v_mfma_f32_32x32x16_bf16 v[2:17], v[216:219], v[230:233], v[2:17]
	s_cbranch_scc1 .LBB0_196
	v_lshlrev_b32_e32 v193, 2, v193
	v_sub_u32_e32 v193, v194, v193
	v_add_u32_e32 v193, s86, v193
	v_add_u32_e32 v195, 0x7fffffc1, v193
	v_cmp_gt_u32_e32 vcc, s46, v195
	s_nop 4
	v_cndmask_b32_e32 v18, v225, v18, vcc
	v_cmp_lt_i32_e32 vcc, 31, v195
	s_nop 1
	v_cndmask_b32_e32 v2, v225, v2, vcc
	v_cmp_lt_i32_e32 vcc, 0, v195
	v_add_u32_e32 v195, 0xffffffa1, v193
	s_nop 0
	v_cndmask_b32_e32 v19, v225, v19, vcc
	v_cmp_lt_u32_e32 vcc, s49, v195
	v_subrev_u32_e32 v195, 64, v193
	s_nop 0
	v_cndmask_b32_e32 v3, v225, v3, vcc
	v_cmp_lt_u32_e32 vcc, s49, v195
	v_add_u32_e32 v195, 0xffffffa0, v193
	s_nop 0
	v_cndmask_b32_e32 v20, v225, v20, vcc
	v_cmp_lt_u32_e32 vcc, s49, v195
	v_add_u32_e32 v195, 0xffffffbf, v193
	s_nop 0
	v_cndmask_b32_e32 v4, v225, v4, vcc
	v_cmp_lt_u32_e32 vcc, s49, v195
	v_add_u32_e32 v195, 0xffffff9f, v193
	s_nop 0
	v_cndmask_b32_e32 v21, v225, v21, vcc
	v_cmp_lt_u32_e32 vcc, s49, v195
	v_add_u32_e32 v195, 0xffffffba, v193
	s_nop 0
	v_cndmask_b32_e32 v5, v225, v5, vcc
	v_cmp_lt_u32_e32 vcc, s49, v195
	v_add_u32_e32 v195, 0xffffff9a, v193
	s_nop 0
	v_cndmask_b32_e32 v22, v225, v22, vcc
	v_cmp_lt_u32_e32 vcc, s49, v195
	v_add_u32_e32 v195, 0xffffffb9, v193
	s_nop 0
	v_cndmask_b32_e32 v6, v225, v6, vcc
	v_cmp_lt_u32_e32 vcc, s49, v195
	v_add_u32_e32 v195, 0xffffff99, v193
	s_nop 0
	v_cndmask_b32_e32 v23, v225, v23, vcc
	v_cmp_lt_u32_e32 vcc, s49, v195
	v_add_u32_e32 v195, 0xffffffb8, v193
	s_nop 0
	v_cndmask_b32_e32 v7, v225, v7, vcc
	v_cmp_lt_u32_e32 vcc, s49, v195
	v_add_u32_e32 v195, 0xffffff98, v193
	s_nop 0
	v_cndmask_b32_e32 v24, v225, v24, vcc
	v_cmp_lt_u32_e32 vcc, s49, v195
	v_add_u32_e32 v195, 0xffffffb7, v193
	s_nop 0
	v_cndmask_b32_e32 v8, v225, v8, vcc
	v_cmp_lt_u32_e32 vcc, s49, v195
	v_add_u32_e32 v195, 0xffffff97, v193
	s_nop 0
	v_cndmask_b32_e32 v25, v225, v25, vcc
	v_cmp_lt_u32_e32 vcc, s49, v195
	v_add_u32_e32 v195, 0xffffffb2, v193
	s_nop 0
	v_cndmask_b32_e32 v9, v225, v9, vcc
	v_cmp_lt_u32_e32 vcc, s49, v195
	v_add_u32_e32 v195, 0xffffff92, v193
	s_nop 0
	v_cndmask_b32_e32 v26, v225, v26, vcc
	v_cmp_lt_u32_e32 vcc, s49, v195
	v_add_u32_e32 v195, 0xffffffb1, v193
	s_nop 0
	v_cndmask_b32_e32 v10, v225, v10, vcc
	v_cmp_lt_u32_e32 vcc, s49, v195
	v_add_u32_e32 v195, 0xffffff91, v193
	s_nop 0
	v_cndmask_b32_e32 v27, v225, v27, vcc
	v_cmp_lt_u32_e32 vcc, s49, v195
	v_add_u32_e32 v195, 0xffffffb0, v193
	s_nop 0
	v_cndmask_b32_e32 v11, v225, v11, vcc
	v_cmp_lt_u32_e32 vcc, s49, v195
	v_add_u32_e32 v195, 0xffffff90, v193
	s_nop 0
	v_cndmask_b32_e32 v28, v225, v28, vcc
	v_cmp_lt_u32_e32 vcc, s49, v195
	v_add_u32_e32 v195, 0xffffffaf, v193
	s_nop 0
	v_cndmask_b32_e32 v12, v225, v12, vcc
	v_cmp_lt_u32_e32 vcc, s49, v195
	v_add_u32_e32 v195, 0xffffff8f, v193
	s_nop 0
	v_cndmask_b32_e32 v29, v225, v29, vcc
	v_cmp_lt_u32_e32 vcc, s49, v195
	v_add_u32_e32 v195, 0xffffffaa, v193
	s_nop 0
	v_cndmask_b32_e32 v13, v225, v13, vcc
	v_cmp_lt_u32_e32 vcc, s49, v195
	v_add_u32_e32 v195, 0xffffff8a, v193
	s_nop 0
	v_cndmask_b32_e32 v30, v225, v30, vcc
	v_cmp_lt_u32_e32 vcc, s49, v195
	v_add_u32_e32 v195, 0xffffffa9, v193
	s_nop 0
	v_cndmask_b32_e32 v14, v225, v14, vcc
	v_cmp_lt_u32_e32 vcc, s49, v195
	v_add_u32_e32 v195, 0xffffff89, v193
	s_nop 0
	v_cndmask_b32_e32 v31, v225, v31, vcc
	v_cmp_lt_u32_e32 vcc, s49, v195
	v_add_u32_e32 v195, 0xffffffa8, v193
	s_nop 0
	v_cndmask_b32_e32 v15, v225, v15, vcc
	v_cmp_lt_u32_e32 vcc, s49, v195
	v_add_u32_e32 v195, 0xffffff88, v193
	s_nop 0
	v_cndmask_b32_e32 v32, v225, v32, vcc
	v_cmp_lt_u32_e32 vcc, s49, v195
	v_add_u32_e32 v195, 0xffffffa7, v193
	v_add_u32_e32 v193, 0xffffff87, v193
	v_cndmask_b32_e32 v16, v225, v16, vcc
	v_cmp_lt_u32_e32 vcc, s49, v195
	s_nop 1
	v_cndmask_b32_e32 v33, v225, v33, vcc
	v_cmp_lt_u32_e32 vcc, s49, v193
	s_nop 1
	v_cndmask_b32_e32 v17, v225, v17, vcc
